# mixer pass-2 entry-state rebuild (HGRN chains): the sixteen loads per earlier segment issued together with progressive waits
# speedup vs baseline: 1.0226x; 1.0074x over previous
.LBB0_466:
	s_ashr_i32 s3, s2, 31
	s_lshl_b64 s[38:39], s[2:3], 9
	v_lshl_add_u64 v[70:71], v[0:1], 0, s[38:39]
	global_load_dwordx4 v[140:143], v[70:71], off
	global_load_dwordx4 v[144:147], v[68:69], off
	global_load_dwordx4 v[148:151], v[70:71], off offset:64
	v_add_co_u32_e32 v100, vcc, s97, v68
	v_addc_co_u32_e32 v101, vcc, 0, v69, vcc
	global_load_dwordx4 v[152:155], v[100:101], off offset:-4096
	global_load_dwordx4 v[156:159], v[70:71], off offset:128
	global_load_dwordx4 v[160:163], v[100:101], off
	global_load_dwordx4 v[164:167], v[70:71], off offset:192
	v_add_co_u32_e32 v102, vcc, s4, v68
	v_addc_co_u32_e32 v103, vcc, 0, v69, vcc
	global_load_dwordx4 v[168:171], v[102:103], off offset:-4096
	global_load_dwordx4 v[172:175], v[70:71], off offset:256
	global_load_dwordx4 v[176:179], v[102:103], off
	global_load_dwordx4 v[180:183], v[70:71], off offset:320
	v_add_co_u32_e32 v104, vcc, s5, v68
	v_addc_co_u32_e32 v105, vcc, 0, v69, vcc
	global_load_dwordx4 v[184:187], v[104:105], off offset:-4096
	global_load_dwordx4 v[188:191], v[70:71], off offset:384
	global_load_dwordx4 v[88:91], v[104:105], off
	global_load_dwordx4 v[92:95], v[70:71], off offset:448
	v_add_co_u32_e32 v106, vcc, s6, v68
	v_addc_co_u32_e32 v107, vcc, 0, v69, vcc
	global_load_dwordx4 v[96:99], v[106:107], off
	s_waitcnt vmcnt(15)
	s_add_i32 s27, s27, -1
	s_add_i32 s2, s2, 1
	s_cmp_lg_u32 s27, 0
	v_mul_f32_e32 v3, 0x3fb8aa3b, v140
	v_exp_f32_e32 v78, v3
	v_mul_f32_e32 v3, 0x3fb8aa3b, v141
	v_exp_f32_e32 v79, v3
	v_mul_f32_e32 v3, 0x3fb8aa3b, v142
	v_exp_f32_e32 v80, v3
	v_mul_f32_e32 v3, 0x3fb8aa3b, v143
	s_waitcnt vmcnt(14)
	v_exp_f32_e32 v81, v3
	v_lshlrev_b32_e32 v82, 16, v144
	v_and_b32_e32 v83, 0xffff0000, v144
	v_lshlrev_b32_e32 v74, 16, v145
	v_and_b32_e32 v75, 0xffff0000, v145
	v_pk_fma_f32 v[6:7], v[6:7], v[80:81], v[74:75]
	v_lshlrev_b32_e32 v74, 16, v146
	v_and_b32_e32 v75, 0xffff0000, v146
	v_lshlrev_b32_e32 v76, 16, v147
	v_and_b32_e32 v77, 0xffff0000, v147
	v_pk_fma_f32 v[10:11], v[10:11], v[80:81], v[76:77]
	v_pk_fma_f32 v[8:9], v[8:9], v[78:79], v[74:75]
	s_waitcnt vmcnt(13)
	v_pk_fma_f32 v[4:5], v[4:5], v[78:79], v[82:83]
	v_mul_f32_e32 v3, 0x3fb8aa3b, v148
	v_exp_f32_e32 v78, v3
	v_mul_f32_e32 v3, 0x3fb8aa3b, v149
	v_exp_f32_e32 v79, v3
	v_mul_f32_e32 v3, 0x3fb8aa3b, v150
	v_exp_f32_e32 v80, v3
	v_mul_f32_e32 v3, 0x3fb8aa3b, v151
	s_waitcnt vmcnt(12)
	v_exp_f32_e32 v81, v3
	v_lshlrev_b32_e32 v84, 16, v152
	v_and_b32_e32 v85, 0xffff0000, v152
	v_lshlrev_b32_e32 v74, 16, v153
	v_and_b32_e32 v75, 0xffff0000, v153
	v_pk_fma_f32 v[14:15], v[14:15], v[80:81], v[74:75]
	v_lshlrev_b32_e32 v74, 16, v154
	v_and_b32_e32 v75, 0xffff0000, v154
	v_lshlrev_b32_e32 v76, 16, v155
	v_and_b32_e32 v77, 0xffff0000, v155
	v_pk_fma_f32 v[18:19], v[18:19], v[80:81], v[76:77]
	v_pk_fma_f32 v[16:17], v[16:17], v[78:79], v[74:75]
	s_waitcnt vmcnt(11)
	v_pk_fma_f32 v[12:13], v[12:13], v[78:79], v[84:85]
	v_mul_f32_e32 v3, 0x3fb8aa3b, v156
	v_exp_f32_e32 v78, v3
	v_mul_f32_e32 v3, 0x3fb8aa3b, v157
	v_exp_f32_e32 v79, v3
	v_mul_f32_e32 v3, 0x3fb8aa3b, v158
	v_exp_f32_e32 v80, v3
	v_mul_f32_e32 v3, 0x3fb8aa3b, v159
	s_waitcnt vmcnt(10)
	v_exp_f32_e32 v81, v3
	v_lshlrev_b32_e32 v82, 16, v160
	v_and_b32_e32 v83, 0xffff0000, v160
	v_lshlrev_b32_e32 v74, 16, v161
	v_and_b32_e32 v75, 0xffff0000, v161
	v_pk_fma_f32 v[22:23], v[22:23], v[80:81], v[74:75]
	v_lshlrev_b32_e32 v74, 16, v162
	v_and_b32_e32 v75, 0xffff0000, v162
	v_lshlrev_b32_e32 v76, 16, v163
	v_and_b32_e32 v77, 0xffff0000, v163
	v_pk_fma_f32 v[26:27], v[26:27], v[80:81], v[76:77]
	v_pk_fma_f32 v[24:25], v[24:25], v[78:79], v[74:75]
	s_waitcnt vmcnt(9)
	v_pk_fma_f32 v[20:21], v[20:21], v[78:79], v[82:83]
	v_mul_f32_e32 v3, 0x3fb8aa3b, v164
	v_exp_f32_e32 v78, v3
	v_mul_f32_e32 v3, 0x3fb8aa3b, v165
	v_exp_f32_e32 v79, v3
	v_mul_f32_e32 v3, 0x3fb8aa3b, v166
	v_exp_f32_e32 v80, v3
	v_mul_f32_e32 v3, 0x3fb8aa3b, v167
	s_waitcnt vmcnt(8)
	v_exp_f32_e32 v81, v3
	v_lshlrev_b32_e32 v84, 16, v168
	v_and_b32_e32 v85, 0xffff0000, v168
	v_lshlrev_b32_e32 v74, 16, v169
	v_and_b32_e32 v75, 0xffff0000, v169
	v_pk_fma_f32 v[30:31], v[30:31], v[80:81], v[74:75]
	v_lshlrev_b32_e32 v74, 16, v170
	v_and_b32_e32 v75, 0xffff0000, v170
	v_lshlrev_b32_e32 v76, 16, v171
	v_and_b32_e32 v77, 0xffff0000, v171
	v_pk_fma_f32 v[34:35], v[34:35], v[80:81], v[76:77]
	v_pk_fma_f32 v[32:33], v[32:33], v[78:79], v[74:75]
	s_waitcnt vmcnt(7)
	v_pk_fma_f32 v[28:29], v[28:29], v[78:79], v[84:85]
	v_mul_f32_e32 v3, 0x3fb8aa3b, v172
	v_exp_f32_e32 v78, v3
	v_mul_f32_e32 v3, 0x3fb8aa3b, v173
	v_exp_f32_e32 v79, v3
	v_mul_f32_e32 v3, 0x3fb8aa3b, v174
	v_exp_f32_e32 v80, v3
	v_mul_f32_e32 v3, 0x3fb8aa3b, v175
	s_waitcnt vmcnt(6)
	v_exp_f32_e32 v81, v3
	v_lshlrev_b32_e32 v82, 16, v176
	v_and_b32_e32 v83, 0xffff0000, v176
	v_lshlrev_b32_e32 v74, 16, v177
	v_and_b32_e32 v75, 0xffff0000, v177
	v_pk_fma_f32 v[38:39], v[38:39], v[80:81], v[74:75]
	v_lshlrev_b32_e32 v74, 16, v178
	v_and_b32_e32 v75, 0xffff0000, v178
	v_lshlrev_b32_e32 v76, 16, v179
	v_and_b32_e32 v77, 0xffff0000, v179
	v_pk_fma_f32 v[42:43], v[42:43], v[80:81], v[76:77]
	v_pk_fma_f32 v[40:41], v[40:41], v[78:79], v[74:75]
	s_waitcnt vmcnt(5)
	v_pk_fma_f32 v[36:37], v[36:37], v[78:79], v[82:83]
	v_mul_f32_e32 v3, 0x3fb8aa3b, v180
	v_exp_f32_e32 v78, v3
	v_mul_f32_e32 v3, 0x3fb8aa3b, v181
	v_exp_f32_e32 v79, v3
	v_mul_f32_e32 v3, 0x3fb8aa3b, v182
	v_exp_f32_e32 v80, v3
	v_mul_f32_e32 v3, 0x3fb8aa3b, v183
	s_waitcnt vmcnt(4)
	v_exp_f32_e32 v81, v3
	v_lshlrev_b32_e32 v84, 16, v184
	v_and_b32_e32 v85, 0xffff0000, v184
	v_lshlrev_b32_e32 v74, 16, v185
	v_and_b32_e32 v75, 0xffff0000, v185
	v_pk_fma_f32 v[46:47], v[46:47], v[80:81], v[74:75]
	v_lshlrev_b32_e32 v74, 16, v186
	v_and_b32_e32 v75, 0xffff0000, v186
	v_lshlrev_b32_e32 v76, 16, v187
	v_and_b32_e32 v77, 0xffff0000, v187
	v_pk_fma_f32 v[50:51], v[50:51], v[80:81], v[76:77]
	v_pk_fma_f32 v[48:49], v[48:49], v[78:79], v[74:75]
	s_waitcnt vmcnt(3)
	v_pk_fma_f32 v[44:45], v[44:45], v[78:79], v[84:85]
	v_mul_f32_e32 v3, 0x3fb8aa3b, v188
	v_exp_f32_e32 v78, v3
	v_mul_f32_e32 v3, 0x3fb8aa3b, v189
	v_exp_f32_e32 v79, v3
	v_mul_f32_e32 v3, 0x3fb8aa3b, v190
	v_exp_f32_e32 v80, v3
	v_mul_f32_e32 v3, 0x3fb8aa3b, v191
	s_waitcnt vmcnt(2)
	v_exp_f32_e32 v81, v3
	v_lshlrev_b32_e32 v82, 16, v88
	v_and_b32_e32 v83, 0xffff0000, v88
	v_lshlrev_b32_e32 v74, 16, v89
	v_and_b32_e32 v75, 0xffff0000, v89
	v_pk_fma_f32 v[54:55], v[54:55], v[80:81], v[74:75]
	v_lshlrev_b32_e32 v74, 16, v90
	v_and_b32_e32 v75, 0xffff0000, v90
	v_lshlrev_b32_e32 v76, 16, v91
	v_and_b32_e32 v77, 0xffff0000, v91
	v_pk_fma_f32 v[58:59], v[58:59], v[80:81], v[76:77]
	v_pk_fma_f32 v[56:57], v[56:57], v[78:79], v[74:75]
	s_waitcnt vmcnt(1)
	v_pk_fma_f32 v[52:53], v[52:53], v[78:79], v[82:83]
	v_mul_f32_e32 v3, 0x3fb8aa3b, v92
	v_exp_f32_e32 v70, v3
	v_mul_f32_e32 v3, 0x3fb8aa3b, v93
	v_exp_f32_e32 v71, v3
	v_mul_f32_e32 v3, 0x3fb8aa3b, v94
	v_exp_f32_e32 v78, v3
	v_mul_f32_e32 v3, 0x3fb8aa3b, v95
	s_waitcnt vmcnt(0)
	v_exp_f32_e32 v79, v3
	v_lshl_add_u64 v[68:69], v[68:69], 0, s[8:9]
	v_lshlrev_b32_e32 v80, 16, v96
	v_and_b32_e32 v81, 0xffff0000, v96
	v_lshlrev_b32_e32 v74, 16, v97
	v_and_b32_e32 v75, 0xffff0000, v97
	v_pk_fma_f32 v[62:63], v[62:63], v[78:79], v[74:75]
	v_lshlrev_b32_e32 v74, 16, v98
	v_and_b32_e32 v75, 0xffff0000, v98
	v_lshlrev_b32_e32 v76, 16, v99
	v_and_b32_e32 v77, 0xffff0000, v99
	v_pk_fma_f32 v[60:61], v[60:61], v[70:71], v[80:81]
	v_pk_fma_f32 v[66:67], v[66:67], v[78:79], v[76:77]
	v_pk_fma_f32 v[64:65], v[64:65], v[70:71], v[74:75]
	s_cbranch_scc1 .LBB0_466
